# final RMSNorm fused into E_DOWN epilogue: per-row f64 atomic word carries adder count + sum of squares; phase 15 only sample rows; ss1 re-zeroed at phase 13
# speedup vs baseline: 1.0610x; 1.0079x over previous
; __device__ __forceinline__ int tid_opaque() { int t = threadIdx.x; asm volatile("" : "+v"(t)); return t; }
; __device__ __forceinline__ void phase_final(CParams& p) {
;     const int tid = tid_opaque(), wid = tid >> 6, lane = tid & 63;
;     const int gw = blockIdx.x * 8 + wid, nw = gridDim.x * 8;
;     f32x4 gfin[4];
; #pragma unroll
;     for (int i = 0; i < 4; ++i) gfin[i] = *(const f32x4*)(p.in[I_GFIN] + lane * 4 + i * 256);
;     for (int row0 = gw; row0 < M; row0 += 2 * nw) {
;         f32x4 v[2][4]; float sv[2];
; #pragma unroll
;         for (int b = 0; b < 2; ++b) { const int rr = row0 + b * nw, row = rr < M ? rr : row0;
; __global__ void __launch_bounds__(512, 2) mega(Params p_unused) {
;     ...
;         switch (ph) {
;         case 0: phase_prep(p, lds); break;
;         case 2: phase_conv(p, lds); break;
;         case 4: phase_scan(p, lds); break;
;         case 5: phase_yn(p, lds); break;
;         case 15: phase_final(p); break;
.LBB0_8:
	v_readlane_b32 s0, v246, 2
	s_cmp_lg_u32 s0, 13
	s_cbranch_scc1 .Lz_skip
	s_load_dwordx2 s[0:1], s[62:63], 0x1a8
	s_mul_i32 s4, s93, 0x204
	v_mov_b32_e32 v1, 0
	v_cmp_gt_u32_e32 vcc, 0x81, v192
	v_lshl_add_u32 v0, v192, 2, s4
	s_and_saveexec_b64 s[4:5], vcc
	s_waitcnt lgkmcnt(0)
	global_store_dword v0, v1, s[0:1]
	s_or_b64 exec, exec, s[4:5]
.Lz_skip:
	v_readlane_b32 s0, v246, 2
	s_mov_b32 s43, s0
	s_cmp_lt_i32 s0, 4
	s_mov_b64 s[4:5], -1
	v_readlane_b32 s1, v246, 3
	v_writelane_b32 v244, s43, 8
	s_cbranch_scc1 .LBB0_187
	s_cmp_lt_i32 s43, 5
	s_cbranch_scc1 .LBB0_128
	s_cmp_lt_i32 s43, 15
	s_cbranch_scc1 .LBB0_19
	s_cmp_eq_u32 s43, 15
	s_cbranch_scc0 .LBB0_18
	s_waitcnt vmcnt(0)
	v_mov_b32_e32 v0, v192
	v_readlane_b32 s0, v246, 4
	v_ashrrev_i32_e32 v1, 6, v0
	s_nop 0
	v_add_u32_e32 v16, s0, v1
	v_add_u32_e32 v16, 0x8000, v16
	s_mov_b32 s0, 0x8100
	v_cmp_gt_i32_e32 vcc, s0, v16
	s_and_saveexec_b64 s[4:5], vcc
	s_cbranch_execz .LBB0_17
	s_load_dwordx4 s[0:3], s[62:63], 0x130
	v_lshlrev_b32_e32 v0, 4, v0
	v_and_b32_e32 v160, 0x3f0, v0
	s_mov_b64 s[8:9], 0
	s_waitcnt lgkmcnt(0)
	global_load_dwordx4 v[0:3], v160, s[0:1]
	global_load_dwordx4 v[4:7], v160, s[0:1] offset:1024
	global_load_dwordx4 v[8:11], v160, s[0:1] offset:2048
	global_load_dwordx4 v[12:15], v160, s[0:1] offset:3072
	v_lshl_add_u64 v[48:49], s[2:3], 0, v[160:161]
	s_branch .LBB0_15

; #define PG8_STAGE(bufoff, gbase, voff) do { _Pragma("unroll") for (int _i = 0; _i < 2; ++_i) \
;         __builtin_amdgcn_global_load_lds((const unsigned*)((const char*)(gbase) + (voff)[_i]), (LAS unsigned*)(lds + (bufoff) + ldsw + _i * 8192), 16, 0, 0); } while (0)
; #define PG8_LDA(dst, b, h) do { _Pragma("unroll") for (int m = 0; m < 4; ++m) _Pragma("unroll") for (int k = 0; k < 2; ++k) dst[m][k] = *(const LAS bf16x8*)(lds + PG8_SA(b, h) + aoff + m * 2048 + k * 1024); } while (0)
; #define PG8_WAIT_V(n) asm volatile("s_waitcnt vmcnt(" #n ")" ::: "memory")
; #define PG8_WAIT_L(n) asm volatile("s_waitcnt lgkmcnt(" #n ")" ::: "memory")
; #define PG8_BAR __builtin_amdgcn_s_barrier()
; __device__ __forceinline__ void gemm_phase(LAS unsigned char* lds, CParams& p, const Job& jb) {
;     ...
;         for (int t = 0; t < nt; t += 2) {
;             const bool last = (t == nt - 2);
;             const char* a1 = cA + (size_t)(t + 1) * kstep;
;             const char* a2 = last ? nA : cA + (size_t)(t + 2) * kstep; const char* b2 = last ? nB : cB + (size_t)(t + 2) * kstep;
;             const char* a3 = a2 + kstep; const char* b3 = b2 + kstep;
;             PG8_LDB(B0, 0, 0); PG8_SCHED; PG8_LDA(At, 0, 0); PG8_STAGE(PG8_SA(1, 1), a1 + hstepA, voffA);
;             PG8_WAIT_L(8); PG8_BAR; PG8_WAIT_L(0); PG8_MMA(0, 0, At, B0); PG8_BAR; PG8_SCHED;
;             PG8_LDB(B1, 0, 1); PG8_STAGE(PG8_SB(0, 0), b2, voffB);
;             PG8_BAR; PG8_WAIT_L(0); PG8_MMA(0, 1, At, B1); PG8_BAR;
;             PG8_LDA(At, 0, 1); PG8_STAGE(PG8_SA(0, 0), a2, voffA);
;             PG8_BAR; PG8_WAIT_L(0); PG8_MMA(1, 0, At, B0); PG8_BAR; PG8_SCHED;
;             PG8_STAGE(PG8_SB(0, 1), b2 + hstepB, voffB);
;             PG8_WAIT_V(6); PG8_BAR; PG8_MMA(1, 1, At, B1); PG8_BAR;
;             PG8_LDB(B0, 1, 0); PG8_SCHED; PG8_LDA(At, 1, 0); PG8_STAGE(PG8_SA(0, 1), a2 + hstepA, voffA);
;             PG8_WAIT_L(8); PG8_BAR; PG8_WAIT_L(0); PG8_MMA(0, 0, At, B0); PG8_BAR; PG8_SCHED;
;             PG8_LDB(B1, 1, 1); PG8_STAGE(PG8_SB(1, 0), b3, voffB);
;             PG8_BAR; PG8_WAIT_L(0); PG8_MMA(0, 1, At, B1); PG8_BAR;
;             PG8_LDA(At, 1, 1); PG8_STAGE(PG8_SA(1, 0), a3, voffA);
;             PG8_BAR; PG8_WAIT_L(0); PG8_MMA(1, 0, At, B0); PG8_BAR; PG8_SCHED;
;             PG8_STAGE(PG8_SB(1, 1), b3 + hstepB, voffB);
;             PG8_WAIT_V(6); PG8_BAR; PG8_MMA(1, 1, At, B1); PG8_BAR;
.LBB0_631:
	s_add_i32 s1, s1, 2
	s_add_u32 s12, s24, s10
	s_addc_u32 s13, s25, s11
	s_add_u32 s12, s12, 0x100
	s_addc_u32 s13, s13, 0
	s_add_u32 s14, s97, s10
	s_addc_u32 s15, s2, s11
	s_add_i32 s16, 0, 0x10000
	v_add_u32_e32 v144, s16, v213
	ds_read_b128 v[132:135], v144
	ds_read_b128 v[136:139], v144 offset:1024
	ds_read_b128 v[140:143], v144 offset:2048
	ds_read_b128 v[144:147], v144 offset:3072
	s_cmp_eq_u32 s85, s10
	s_cselect_b32 s13, s5, s13
	s_cselect_b32 s12, s4, s12
	s_cselect_b32 s15, s87, s15
	s_cselect_b32 s14, s86, s14
	v_lshl_add_u64 v[216:217], v[128:129], 0, s[10:11]
	s_add_i32 m0, s65, 0xc000
	ds_read_b128 v[148:151], v214
	ds_read_b128 v[152:155], v214 offset:1024
	ds_read_b128 v[156:159], v214 offset:2048
	ds_read_b128 v[172:175], v214 offset:3072
	ds_read_b128 v[176:179], v214 offset:4096
	ds_read_b128 v[180:183], v214 offset:5120
	ds_read_b128 v[184:187], v214 offset:6144
	ds_read_b128 v[188:191], v214 offset:7168
	global_load_lds_dwordx4 v[216:217], off
	v_lshl_add_u64 v[216:217], v[130:131], 0, s[10:11]
	s_add_i32 m0, s65, 0xe000
	s_nop 0
	global_load_lds_dwordx4 v[216:217], off
	s_waitcnt lgkmcnt(8)
	s_barrier
	s_waitcnt lgkmcnt(0)
	s_setprio 1
	s_waitcnt lgkmcnt(0)
	v_mfma_f32_16x16x32_bf16 v[124:127], v[132:135], v[148:151], v[124:127]
	v_mfma_f32_16x16x32_bf16 v[120:123], v[140:143], v[148:151], v[120:123]
	v_mfma_f32_16x16x32_bf16 v[116:119], v[132:135], v[156:159], v[116:119]
	v_mfma_f32_16x16x32_bf16 v[112:115], v[140:143], v[156:159], v[112:115]
	v_mfma_f32_16x16x32_bf16 v[108:111], v[132:135], v[176:179], v[108:111]
	v_mfma_f32_16x16x32_bf16 v[104:107], v[140:143], v[176:179], v[104:107]
	v_mfma_f32_16x16x32_bf16 v[100:103], v[132:135], v[184:187], v[100:103]
	v_mfma_f32_16x16x32_bf16 v[96:99], v[140:143], v[184:187], v[96:99]
	v_mfma_f32_16x16x32_bf16 v[124:127], v[136:139], v[152:155], v[124:127]
	v_mfma_f32_16x16x32_bf16 v[120:123], v[144:147], v[152:155], v[120:123]
	v_mfma_f32_16x16x32_bf16 v[116:119], v[136:139], v[172:175], v[116:119]
	v_mfma_f32_16x16x32_bf16 v[112:115], v[144:147], v[172:175], v[112:115]
	v_mfma_f32_16x16x32_bf16 v[108:111], v[136:139], v[180:183], v[108:111]
	v_mfma_f32_16x16x32_bf16 v[104:107], v[144:147], v[180:183], v[104:107]
	v_mfma_f32_16x16x32_bf16 v[100:103], v[136:139], v[188:191], v[100:103]
	v_mfma_f32_16x16x32_bf16 v[96:99], v[144:147], v[188:191], v[96:99]
	s_setprio 0
	s_barrier
	s_add_i32 s17, 0, 0x14000
	s_add_i32 s16, s16, s64
	v_add_u32_e32 v215, s17, v213
	v_lshl_add_u64 v[232:233], s[14:15], 0, v[160:161]
	s_mov_b32 m0, s16
	ds_read_b128 v[216:219], v215
	ds_read_b128 v[220:223], v215 offset:1024
	ds_read_b128 v[224:227], v215 offset:2048
	ds_read_b128 v[228:231], v215 offset:3072
	global_load_lds_dwordx4 v[232:233], off
	v_lshl_add_u64 v[234:235], s[14:15], 0, v[166:167]
	s_add_i32 m0, s16, 0x2000
	s_nop 0
	global_load_lds_dwordx4 v[234:235], off
	s_barrier
	s_waitcnt lgkmcnt(0)
	s_setprio 1
	s_waitcnt lgkmcnt(0)
	v_mfma_f32_16x16x32_bf16 v[92:95], v[216:219], v[148:151], v[92:95]
	v_mfma_f32_16x16x32_bf16 v[88:91], v[224:227], v[148:151], v[88:91]
	v_mfma_f32_16x16x32_bf16 v[84:87], v[216:219], v[156:159], v[84:87]
	v_mfma_f32_16x16x32_bf16 v[80:83], v[224:227], v[156:159], v[80:83]
	v_mfma_f32_16x16x32_bf16 v[76:79], v[216:219], v[176:179], v[76:79]
	v_mfma_f32_16x16x32_bf16 v[72:75], v[224:227], v[176:179], v[72:75]
	v_mfma_f32_16x16x32_bf16 v[68:71], v[216:219], v[184:187], v[68:71]
	v_mfma_f32_16x16x32_bf16 v[64:67], v[224:227], v[184:187], v[64:67]
	v_mfma_f32_16x16x32_bf16 v[92:95], v[220:223], v[152:155], v[92:95]
	v_mfma_f32_16x16x32_bf16 v[88:91], v[228:231], v[152:155], v[88:91]
	v_mfma_f32_16x16x32_bf16 v[84:87], v[220:223], v[172:175], v[84:87]
	v_mfma_f32_16x16x32_bf16 v[80:83], v[228:231], v[172:175], v[80:83]
	v_mfma_f32_16x16x32_bf16 v[76:79], v[220:223], v[180:183], v[76:79]
	v_mfma_f32_16x16x32_bf16 v[72:75], v[228:231], v[180:183], v[72:75]
	v_mfma_f32_16x16x32_bf16 v[68:71], v[220:223], v[188:191], v[68:71]
	v_mfma_f32_16x16x32_bf16 v[64:67], v[228:231], v[188:191], v[64:67]
	s_setprio 0
	s_mov_b32 m0, s65
	v_lshl_add_u64 v[236:237], s[12:13], 0, v[162:163]
	s_barrier
	ds_read_b128 v[148:151], v214 offset:16384
	ds_read_b128 v[152:155], v214 offset:17408
	ds_read_b128 v[156:159], v214 offset:18432
	ds_read_b128 v[172:175], v214 offset:19456
	ds_read_b128 v[176:179], v214 offset:20480
	ds_read_b128 v[180:183], v214 offset:21504
	ds_read_b128 v[184:187], v214 offset:22528
	ds_read_b128 v[188:191], v214 offset:23552
	global_load_lds_dwordx4 v[236:237], off
	v_lshl_add_u64 v[238:239], s[12:13], 0, v[164:165]
	s_mov_b32 m0, s66
	s_nop 0
	global_load_lds_dwordx4 v[238:239], off
	s_barrier
	s_waitcnt lgkmcnt(0)
	s_setprio 1
	s_waitcnt lgkmcnt(0)
	v_mfma_f32_16x16x32_bf16 v[60:63], v[132:135], v[148:151], v[60:63]
	v_mfma_f32_16x16x32_bf16 v[56:59], v[140:143], v[148:151], v[56:59]
	v_mfma_f32_16x16x32_bf16 v[52:55], v[132:135], v[156:159], v[52:55]
	v_mfma_f32_16x16x32_bf16 v[48:51], v[140:143], v[156:159], v[48:51]
	v_mfma_f32_16x16x32_bf16 v[44:47], v[132:135], v[176:179], v[44:47]
	v_mfma_f32_16x16x32_bf16 v[40:43], v[140:143], v[176:179], v[40:43]
	v_mfma_f32_16x16x32_bf16 v[36:39], v[132:135], v[184:187], v[36:39]
	v_mfma_f32_16x16x32_bf16 v[32:35], v[140:143], v[184:187], v[32:35]
	v_mfma_f32_16x16x32_bf16 v[60:63], v[136:139], v[152:155], v[60:63]
	v_mfma_f32_16x16x32_bf16 v[56:59], v[144:147], v[152:155], v[56:59]
	v_mfma_f32_16x16x32_bf16 v[52:55], v[136:139], v[172:175], v[52:55]
	v_mfma_f32_16x16x32_bf16 v[48:51], v[144:147], v[172:175], v[48:51]
	v_mfma_f32_16x16x32_bf16 v[44:47], v[136:139], v[180:183], v[44:47]
	v_mfma_f32_16x16x32_bf16 v[40:43], v[144:147], v[180:183], v[40:43]
	v_mfma_f32_16x16x32_bf16 v[36:39], v[136:139], v[188:191], v[36:39]
	v_mfma_f32_16x16x32_bf16 v[32:35], v[144:147], v[188:191], v[32:35]
	s_setprio 0
	s_barrier
; #define PG8_STAGE(bufoff, gbase, voff) do { _Pragma("unroll") for (int _i = 0; _i < 2; ++_i) \
;         __builtin_amdgcn_global_load_lds((const unsigned*)((const char*)(gbase) + (voff)[_i]), (LAS unsigned*)(lds + (bufoff) + ldsw + _i * 8192), 16, 0, 0); } while (0)
; #define PG8_LDA(dst, b, h) do { _Pragma("unroll") for (int m = 0; m < 4; ++m) _Pragma("unroll") for (int k = 0; k < 2; ++k) dst[m][k] = *(const LAS bf16x8*)(lds + PG8_SA(b, h) + aoff + m * 2048 + k * 1024); } while (0)
; #define PG8_WAIT_V(n) asm volatile("s_waitcnt vmcnt(" #n ")" ::: "memory")
; #define PG8_WAIT_L(n) asm volatile("s_waitcnt lgkmcnt(" #n ")" ::: "memory")
; #define PG8_BAR __builtin_amdgcn_s_barrier()
; __device__ __forceinline__ void gemm_phase(LAS unsigned char* lds, CParams& p, const Job& jb) {
;     ...
;         for (int t = 0; t < nt; t += 2) {
;             const bool last = (t == nt - 2);
;             const char* a1 = cA + (size_t)(t + 1) * kstep;
;             const char* a2 = last ? nA : cA + (size_t)(t + 2) * kstep; const char* b2 = last ? nB : cB + (size_t)(t + 2) * kstep;
;             const char* a3 = a2 + kstep; const char* b3 = b2 + kstep;
;             PG8_LDB(B0, 0, 0); PG8_SCHED; PG8_LDA(At, 0, 0); PG8_STAGE(PG8_SA(1, 1), a1 + hstepA, voffA);
;             PG8_WAIT_L(8); PG8_BAR; PG8_WAIT_L(0); PG8_MMA(0, 0, At, B0); PG8_BAR; PG8_SCHED;
;             PG8_LDB(B1, 0, 1); PG8_STAGE(PG8_SB(0, 0), b2, voffB);
;             PG8_BAR; PG8_WAIT_L(0); PG8_MMA(0, 1, At, B1); PG8_BAR;
;             PG8_LDA(At, 0, 1); PG8_STAGE(PG8_SA(0, 0), a2, voffA);
;             PG8_BAR; PG8_WAIT_L(0); PG8_MMA(1, 0, At, B0); PG8_BAR; PG8_SCHED;
;             PG8_STAGE(PG8_SB(0, 1), b2 + hstepB, voffB);
;             PG8_WAIT_V(6); PG8_BAR; PG8_MMA(1, 1, At, B1); PG8_BAR;
;             PG8_LDB(B0, 1, 0); PG8_SCHED; PG8_LDA(At, 1, 0); PG8_STAGE(PG8_SA(0, 1), a2 + hstepA, voffA);
;             PG8_WAIT_L(8); PG8_BAR; PG8_WAIT_L(0); PG8_MMA(0, 0, At, B0); PG8_BAR; PG8_SCHED;
;             PG8_LDB(B1, 1, 1); PG8_STAGE(PG8_SB(1, 0), b3, voffB);
;             PG8_BAR; PG8_WAIT_L(0); PG8_MMA(0, 1, At, B1); PG8_BAR;
;             PG8_LDA(At, 1, 1); PG8_STAGE(PG8_SA(1, 0), a3, voffA);
;             PG8_BAR; PG8_WAIT_L(0); PG8_MMA(1, 0, At, B0); PG8_BAR; PG8_SCHED;
;             PG8_STAGE(PG8_SB(1, 1), b3 + hstepB, voffB);
;             PG8_WAIT_V(6); PG8_BAR; PG8_MMA(1, 1, At, B1); PG8_BAR;
	s_add_u32 s14, s14, s76
	s_addc_u32 s15, s15, s77
	s_add_i32 s16, s17, s64
	v_lshl_add_u64 v[240:241], s[14:15], 0, v[160:161]
	s_mov_b32 m0, s16
	v_lshl_add_u64 v[242:243], s[14:15], 0, v[166:167]
	global_load_lds_dwordx4 v[240:241], off
	s_add_i32 m0, s16, 0x2000
	s_nop 0
	global_load_lds_dwordx4 v[242:243], off
	s_waitcnt vmcnt(6)
	s_barrier
	s_setprio 1
	v_mfma_f32_16x16x32_bf16 v[28:31], v[216:219], v[148:151], v[28:31]
	v_mfma_f32_16x16x32_bf16 v[24:27], v[224:227], v[148:151], v[24:27]
	v_mfma_f32_16x16x32_bf16 v[20:23], v[216:219], v[156:159], v[20:23]
	v_mfma_f32_16x16x32_bf16 v[16:19], v[224:227], v[156:159], v[16:19]
	v_mfma_f32_16x16x32_bf16 v[12:15], v[216:219], v[176:179], v[12:15]
	v_mfma_f32_16x16x32_bf16 v[8:11], v[224:227], v[176:179], v[8:11]
	v_mfma_f32_16x16x32_bf16 v[4:7], v[216:219], v[184:187], v[4:7]
	v_mfma_f32_16x16x32_bf16 v[0:3], v[224:227], v[184:187], v[0:3]
	v_mfma_f32_16x16x32_bf16 v[28:31], v[220:223], v[152:155], v[28:31]
	v_mfma_f32_16x16x32_bf16 v[24:27], v[228:231], v[152:155], v[24:27]
	v_mfma_f32_16x16x32_bf16 v[20:23], v[220:223], v[172:175], v[20:23]
	v_mfma_f32_16x16x32_bf16 v[16:19], v[228:231], v[172:175], v[16:19]
	v_mfma_f32_16x16x32_bf16 v[12:15], v[220:223], v[180:183], v[12:15]
	v_mfma_f32_16x16x32_bf16 v[8:11], v[228:231], v[180:183], v[8:11]
	v_mfma_f32_16x16x32_bf16 v[4:7], v[220:223], v[188:191], v[4:7]
	v_mfma_f32_16x16x32_bf16 v[0:3], v[228:231], v[188:191], v[0:3]
	s_setprio 0
	s_add_i32 s14, 0, 0x18000
	v_add_u32_e32 v144, s14, v213
	s_barrier
	ds_read_b128 v[132:135], v144
	ds_read_b128 v[136:139], v144 offset:1024
	ds_read_b128 v[140:143], v144 offset:2048
	ds_read_b128 v[144:147], v144 offset:3072
	s_add_u32 s12, s12, s74
	s_addc_u32 s13, s13, s75
	s_mov_b32 m0, s67
	v_lshl_add_u64 v[216:217], s[12:13], 0, v[162:163]
	ds_read_b128 v[148:151], v214 offset:32768
	ds_read_b128 v[152:155], v214 offset:33792
	ds_read_b128 v[156:159], v214 offset:34816
	ds_read_b128 v[172:175], v214 offset:35840
	ds_read_b128 v[176:179], v214 offset:36864
	ds_read_b128 v[180:183], v214 offset:37888
	ds_read_b128 v[184:187], v214 offset:38912
	ds_read_b128 v[188:191], v214 offset:39936
	global_load_lds_dwordx4 v[216:217], off
	v_lshl_add_u64 v[216:217], s[12:13], 0, v[164:165]
	s_mov_b32 m0, s94
	s_nop 0
	global_load_lds_dwordx4 v[216:217], off
	s_waitcnt lgkmcnt(8)
	s_barrier
	s_waitcnt lgkmcnt(0)
	s_setprio 1
	s_waitcnt lgkmcnt(0)
	v_mfma_f32_16x16x32_bf16 v[124:127], v[132:135], v[148:151], v[124:127]
	v_mfma_f32_16x16x32_bf16 v[120:123], v[140:143], v[148:151], v[120:123]
	v_mfma_f32_16x16x32_bf16 v[116:119], v[132:135], v[156:159], v[116:119]
	v_mfma_f32_16x16x32_bf16 v[112:115], v[140:143], v[156:159], v[112:115]
	v_mfma_f32_16x16x32_bf16 v[108:111], v[132:135], v[176:179], v[108:111]
	v_mfma_f32_16x16x32_bf16 v[104:107], v[140:143], v[176:179], v[104:107]
	v_mfma_f32_16x16x32_bf16 v[100:103], v[132:135], v[184:187], v[100:103]
	v_mfma_f32_16x16x32_bf16 v[96:99], v[140:143], v[184:187], v[96:99]
	v_mfma_f32_16x16x32_bf16 v[124:127], v[136:139], v[152:155], v[124:127]
	v_mfma_f32_16x16x32_bf16 v[120:123], v[144:147], v[152:155], v[120:123]
	v_mfma_f32_16x16x32_bf16 v[116:119], v[136:139], v[172:175], v[116:119]
	v_mfma_f32_16x16x32_bf16 v[112:115], v[144:147], v[172:175], v[112:115]
	v_mfma_f32_16x16x32_bf16 v[108:111], v[136:139], v[180:183], v[108:111]
	v_mfma_f32_16x16x32_bf16 v[104:107], v[144:147], v[180:183], v[104:107]
	v_mfma_f32_16x16x32_bf16 v[100:103], v[136:139], v[188:191], v[100:103]
	v_mfma_f32_16x16x32_bf16 v[96:99], v[144:147], v[188:191], v[96:99]
	s_setprio 0
	s_barrier
	s_add_i32 s12, 0, 0x1c000
	s_add_i32 s13, s14, s64
	v_add_u32_e32 v215, s12, v213
	v_lshl_add_u64 v[232:233], v[232:233], 0, s[90:91]
	s_mov_b32 m0, s13
	ds_read_b128 v[216:219], v215
	ds_read_b128 v[220:223], v215 offset:1024
	ds_read_b128 v[224:227], v215 offset:2048
	ds_read_b128 v[228:231], v215 offset:3072
	global_load_lds_dwordx4 v[232:233], off
	v_lshl_add_u64 v[232:233], v[234:235], 0, s[90:91]
	s_add_i32 m0, s13, 0x2000
	s_nop 0
	global_load_lds_dwordx4 v[232:233], off
	s_barrier
	s_waitcnt lgkmcnt(0)
	s_setprio 1
	s_waitcnt lgkmcnt(0)
	v_mfma_f32_16x16x32_bf16 v[92:95], v[216:219], v[148:151], v[92:95]
	v_mfma_f32_16x16x32_bf16 v[88:91], v[224:227], v[148:151], v[88:91]
	v_mfma_f32_16x16x32_bf16 v[84:87], v[216:219], v[156:159], v[84:87]
	v_mfma_f32_16x16x32_bf16 v[80:83], v[224:227], v[156:159], v[80:83]
	v_mfma_f32_16x16x32_bf16 v[76:79], v[216:219], v[176:179], v[76:79]
	v_mfma_f32_16x16x32_bf16 v[72:75], v[224:227], v[176:179], v[72:75]
	v_mfma_f32_16x16x32_bf16 v[68:71], v[216:219], v[184:187], v[68:71]
	v_mfma_f32_16x16x32_bf16 v[64:67], v[224:227], v[184:187], v[64:67]
	v_mfma_f32_16x16x32_bf16 v[92:95], v[220:223], v[152:155], v[92:95]
	v_mfma_f32_16x16x32_bf16 v[88:91], v[228:231], v[152:155], v[88:91]
	v_mfma_f32_16x16x32_bf16 v[84:87], v[220:223], v[172:175], v[84:87]
	v_mfma_f32_16x16x32_bf16 v[80:83], v[228:231], v[172:175], v[80:83]
	v_mfma_f32_16x16x32_bf16 v[76:79], v[220:223], v[180:183], v[76:79]
	v_mfma_f32_16x16x32_bf16 v[72:75], v[228:231], v[180:183], v[72:75]
	v_mfma_f32_16x16x32_bf16 v[68:71], v[220:223], v[188:191], v[68:71]
	v_mfma_f32_16x16x32_bf16 v[64:67], v[228:231], v[188:191], v[64:67]
	s_setprio 0
	s_mov_b32 m0, s33
	v_lshl_add_u64 v[232:233], v[236:237], 0, s[90:91]
	s_barrier
	ds_read_b128 v[148:151], v214 offset:49152
	ds_read_b128 v[152:155], v214 offset:50176
	ds_read_b128 v[156:159], v214 offset:51200
	ds_read_b128 v[172:175], v214 offset:52224
	ds_read_b128 v[176:179], v214 offset:53248
	ds_read_b128 v[180:183], v214 offset:54272
	ds_read_b128 v[184:187], v214 offset:55296
	ds_read_b128 v[188:191], v214 offset:56320
	global_load_lds_dwordx4 v[232:233], off
	v_lshl_add_u64 v[232:233], v[238:239], 0, s[90:91]
	s_mov_b32 m0, s60
	s_nop 0
	global_load_lds_dwordx4 v[232:233], off
	s_barrier
; #define FOR_ROWS _Pragma("unroll") for (int ai = 0; ai < 2; ++ai) _Pragma("unroll") for (int m = 0; m < 4; ++m)
; #define PG8_STAGE(bufoff, gbase, voff) do { _Pragma("unroll") for (int _i = 0; _i < 2; ++_i) \
;         __builtin_amdgcn_global_load_lds((const unsigned*)((const char*)(gbase) + (voff)[_i]), (LAS unsigned*)(lds + (bufoff) + ldsw + _i * 8192), 16, 0, 0); } while (0)
; #define PG8_LDA(dst, b, h) do { _Pragma("unroll") for (int m = 0; m < 4; ++m) _Pragma("unroll") for (int k = 0; k < 2; ++k) dst[m][k] = *(const LAS bf16x8*)(lds + PG8_SA(b, h) + aoff + m * 2048 + k * 1024); } while (0)
; #define PG8_MMA(ai, bj, At, Bt) do { __builtin_amdgcn_s_setprio(1); _Pragma("unroll") for (int m = 0; m < 4; ++m) _Pragma("unroll") for (int n = 0; n < 2; ++n) _Pragma("unroll") for (int k = 0; k < 2; ++k) \
;         acc[ai][bj][m][n] = __builtin_amdgcn_mfma_f32_16x16x32_bf16(Bt[n][k], At[m][k], acc[ai][bj][m][n], 0, 0, 0); __builtin_amdgcn_s_setprio(0); } while (0)
; #define PG8_WAIT_V(n) asm volatile("s_waitcnt vmcnt(" #n ")" ::: "memory")
; #define PG8_WAIT_L(n) asm volatile("s_waitcnt lgkmcnt(" #n ")" ::: "memory")
; #define PG8_BAR __builtin_amdgcn_s_barrier()
; #define PG8_SCHED __builtin_amdgcn_sched_barrier(0)
; __device__ __forceinline__ void epilogue(const int kind, CParams& p, const f32x4 (&acc)[2][2][4][2], const Unit& u, const int wr, const int wc, const int fr_in, const int fq_in) {
;     ...
;     case E_DOWN_HALF: {
;         FOR_ROWS { ROWDEF
; #pragma unroll
;             for (int bj = 0; bj < 2; ++bj) { float* hp = p.out + row * 1024 + u.pn * 256 + bj * 128 + cw;
; #pragma unroll
;                 for (int j = 0; j < 4; ++j) { unsafeAtomicAdd(hp + j, acc[ai][bj][m][0][j]); unsafeAtomicAdd(hp + 4 + j, acc[ai][bj][m][1][j]); } } }
;     } break;
; __device__ __forceinline__ void gemm_phase(LAS unsigned char* lds, CParams& p, const Job& jb) {
;     ...
;             PG8_BAR; PG8_WAIT_L(0); PG8_MMA(0, 1, At, B1); PG8_BAR;
;             PG8_LDA(At, 1, 1); PG8_STAGE(PG8_SA(1, 0), a3, voffA);
;             PG8_BAR; PG8_WAIT_L(0); PG8_MMA(1, 0, At, B0); PG8_BAR; PG8_SCHED;
;             PG8_STAGE(PG8_SB(1, 1), b3 + hstepB, voffB);
;             PG8_WAIT_V(6); PG8_BAR; PG8_MMA(1, 1, At, B1); PG8_BAR;
;         }
;         epilogue(cur.kind, p, acc, cur, wr, wc, fr, fq);
	s_waitcnt lgkmcnt(0)
	s_setprio 1
	s_waitcnt lgkmcnt(0)
	v_mfma_f32_16x16x32_bf16 v[60:63], v[132:135], v[148:151], v[60:63]
	v_mfma_f32_16x16x32_bf16 v[56:59], v[140:143], v[148:151], v[56:59]
	v_mfma_f32_16x16x32_bf16 v[52:55], v[132:135], v[156:159], v[52:55]
	v_mfma_f32_16x16x32_bf16 v[48:51], v[140:143], v[156:159], v[48:51]
	v_mfma_f32_16x16x32_bf16 v[44:47], v[132:135], v[176:179], v[44:47]
	v_mfma_f32_16x16x32_bf16 v[40:43], v[140:143], v[176:179], v[40:43]
	v_mfma_f32_16x16x32_bf16 v[36:39], v[132:135], v[184:187], v[36:39]
	v_mfma_f32_16x16x32_bf16 v[32:35], v[140:143], v[184:187], v[32:35]
	v_mfma_f32_16x16x32_bf16 v[60:63], v[136:139], v[152:155], v[60:63]
	v_mfma_f32_16x16x32_bf16 v[56:59], v[144:147], v[152:155], v[56:59]
	v_mfma_f32_16x16x32_bf16 v[52:55], v[136:139], v[172:175], v[52:55]
	v_mfma_f32_16x16x32_bf16 v[48:51], v[144:147], v[172:175], v[48:51]
	v_mfma_f32_16x16x32_bf16 v[44:47], v[136:139], v[180:183], v[44:47]
	v_mfma_f32_16x16x32_bf16 v[40:43], v[144:147], v[180:183], v[40:43]
	v_mfma_f32_16x16x32_bf16 v[36:39], v[136:139], v[188:191], v[36:39]
	v_mfma_f32_16x16x32_bf16 v[32:35], v[144:147], v[188:191], v[32:35]
	s_setprio 0
	s_barrier
	s_add_i32 s12, s12, s64
	v_lshl_add_u64 v[132:133], v[240:241], 0, s[90:91]
	s_mov_b32 m0, s12
	s_nop 0
	global_load_lds_dwordx4 v[132:133], off
	v_lshl_add_u64 v[132:133], v[242:243], 0, s[90:91]
	s_add_i32 m0, s12, 0x2000
	s_nop 0
	global_load_lds_dwordx4 v[132:133], off
	s_waitcnt vmcnt(6)
	s_barrier
	s_setprio 1
	v_mfma_f32_16x16x32_bf16 v[28:31], v[216:219], v[148:151], v[28:31]
	v_mfma_f32_16x16x32_bf16 v[24:27], v[224:227], v[148:151], v[24:27]
	v_mfma_f32_16x16x32_bf16 v[20:23], v[216:219], v[156:159], v[20:23]
	v_mfma_f32_16x16x32_bf16 v[16:19], v[224:227], v[156:159], v[16:19]
	v_mfma_f32_16x16x32_bf16 v[12:15], v[216:219], v[176:179], v[12:15]
	v_mfma_f32_16x16x32_bf16 v[8:11], v[224:227], v[176:179], v[8:11]
	v_mfma_f32_16x16x32_bf16 v[4:7], v[216:219], v[184:187], v[4:7]
	v_mfma_f32_16x16x32_bf16 v[0:3], v[224:227], v[184:187], v[0:3]
	v_mfma_f32_16x16x32_bf16 v[28:31], v[220:223], v[152:155], v[28:31]
	v_mfma_f32_16x16x32_bf16 v[24:27], v[228:231], v[152:155], v[24:27]
	v_mfma_f32_16x16x32_bf16 v[20:23], v[220:223], v[172:175], v[20:23]
	v_mfma_f32_16x16x32_bf16 v[16:19], v[228:231], v[172:175], v[16:19]
	v_mfma_f32_16x16x32_bf16 v[12:15], v[220:223], v[180:183], v[12:15]
	v_mfma_f32_16x16x32_bf16 v[8:11], v[228:231], v[180:183], v[8:11]
	v_mfma_f32_16x16x32_bf16 v[4:7], v[220:223], v[188:191], v[4:7]
	v_mfma_f32_16x16x32_bf16 v[0:3], v[228:231], v[188:191], v[0:3]
	s_setprio 0
	s_add_u32 s10, s10, 0x100
	s_addc_u32 s11, s11, 0
	s_cmp_ge_u32 s1, s84
	s_barrier
	s_cbranch_scc0 .LBB0_631
	v_mov_b32_e32 v215, v211
	v_mov_b32_e32 v216, v212
	s_cmp_eq_u32 s3, 13
	s_cbranch_scc1 .Lmy_down
	s_cmp_lt_i32 s3, 7
	v_lshl_add_u32 v172, v216, 3, s31
	s_mov_b64 s[10:11], -1
	s_cbranch_scc1 .LBB0_849
	s_cmp_lt_i32 s3, 11
	s_cbranch_scc1 .LBB0_639
	s_cmp_gt_i32 s3, 12
	s_cbranch_scc0 .LBB0_640
	s_cmp_gt_i32 s3, 13
	s_mov_b64 s[26:27], -1
	s_cbranch_scc0 .LBB0_641
	s_cmp_eq_u32 s3, 14
	s_cbranch_scc0 .LBB0_638
	v_add_u32_e32 v128, s0, v215
	s_ashr_i32 s79, s78, 31
	v_ashrrev_i32_e32 v129, 31, v128
	v_lshl_add_u64 v[130:131], v[128:129], 0, s[78:79]
	s_lshl_b32 s10, s92, 8
	v_lshlrev_b64 v[130:131], 12, v[130:131]
	s_ashr_i32 s11, s10, 31
	v_ashrrev_i32_e32 v173, 31, v172
	v_lshl_add_u64 v[130:131], s[82:83], 0, v[130:131]
	s_lshl_b64 s[10:11], s[10:11], 2
	v_lshl_add_u64 v[130:131], v[130:131], 0, s[10:11]
	v_lshlrev_b64 v[132:133], 2, v[172:173]
	v_lshl_add_u64 v[130:131], v[130:131], 0, v[132:133]
	global_atomic_add_f32 v[130:131], v124, off
	global_atomic_add_f32 v[130:131], v120, off offset:16
	global_atomic_add_f32 v[130:131], v125, off offset:4
	global_atomic_add_f32 v[130:131], v121, off offset:20
	global_atomic_add_f32 v[130:131], v126, off offset:8
	global_atomic_add_f32 v[130:131], v122, off offset:24
	global_atomic_add_f32 v[130:131], v127, off offset:12
	global_atomic_add_f32 v[130:131], v123, off offset:28
	global_atomic_add_f32 v[130:131], v92, off offset:512
	global_atomic_add_f32 v[130:131], v88, off offset:528
	global_atomic_add_f32 v[130:131], v93, off offset:516
	global_atomic_add_f32 v[130:131], v89, off offset:532
	global_atomic_add_f32 v[130:131], v94, off offset:520
	global_atomic_add_f32 v[130:131], v90, off offset:536
	global_atomic_add_f32 v[130:131], v95, off offset:524
	global_atomic_add_f32 v[130:131], v91, off offset:540
	v_add_u32_e32 v130, 16, v128
	v_ashrrev_i32_e32 v131, 31, v130
	v_lshl_add_u64 v[130:131], v[130:131], 0, s[78:79]
	v_lshlrev_b64 v[130:131], 12, v[130:131]
	v_lshl_add_u64 v[130:131], s[82:83], 0, v[130:131]
	v_lshl_add_u64 v[130:131], v[130:131], 0, s[10:11]
	v_lshl_add_u64 v[130:131], v[130:131], 0, v[132:133]
	global_atomic_add_f32 v[130:131], v116, off
	global_atomic_add_f32 v[130:131], v112, off offset:16
	global_atomic_add_f32 v[130:131], v117, off offset:4
	global_atomic_add_f32 v[130:131], v113, off offset:20
	global_atomic_add_f32 v[130:131], v118, off offset:8
	global_atomic_add_f32 v[130:131], v114, off offset:24
	global_atomic_add_f32 v[130:131], v119, off offset:12
	global_atomic_add_f32 v[130:131], v115, off offset:28
	global_atomic_add_f32 v[130:131], v84, off offset:512
	global_atomic_add_f32 v[130:131], v80, off offset:528
	global_atomic_add_f32 v[130:131], v85, off offset:516
	global_atomic_add_f32 v[130:131], v81, off offset:532
	global_atomic_add_f32 v[130:131], v86, off offset:520
	global_atomic_add_f32 v[130:131], v82, off offset:536
	global_atomic_add_f32 v[130:131], v87, off offset:524
; #define FOR_ROWS _Pragma("unroll") for (int ai = 0; ai < 2; ++ai) _Pragma("unroll") for (int m = 0; m < 4; ++m)
; __device__ __forceinline__ void epilogue(const int kind, CParams& p, const f32x4 (&acc)[2][2][4][2], const Unit& u, const int wr, const int wc, const int fr_in, const int fq_in) {
;     ...
;     case E_DOWN_HALF: {
;         FOR_ROWS { ROWDEF
; #pragma unroll
;             for (int bj = 0; bj < 2; ++bj) { float* hp = p.out + row * 1024 + u.pn * 256 + bj * 128 + cw;
; #pragma unroll
;                 for (int j = 0; j < 4; ++j) { unsafeAtomicAdd(hp + j, acc[ai][bj][m][0][j]); unsafeAtomicAdd(hp + 4 + j, acc[ai][bj][m][1][j]); } } }
;     } break;
	global_atomic_add_f32 v[130:131], v83, off offset:540
	v_add_u32_e32 v130, 32, v128
	v_ashrrev_i32_e32 v131, 31, v130
	v_lshl_add_u64 v[130:131], v[130:131], 0, s[78:79]
	v_lshlrev_b64 v[130:131], 12, v[130:131]
	v_lshl_add_u64 v[130:131], s[82:83], 0, v[130:131]
	v_lshl_add_u64 v[130:131], v[130:131], 0, s[10:11]
	v_lshl_add_u64 v[130:131], v[130:131], 0, v[132:133]
	global_atomic_add_f32 v[130:131], v108, off
	global_atomic_add_f32 v[130:131], v104, off offset:16
	global_atomic_add_f32 v[130:131], v109, off offset:4
	global_atomic_add_f32 v[130:131], v105, off offset:20
	global_atomic_add_f32 v[130:131], v110, off offset:8
	global_atomic_add_f32 v[130:131], v106, off offset:24
	global_atomic_add_f32 v[130:131], v111, off offset:12
	global_atomic_add_f32 v[130:131], v107, off offset:28
	global_atomic_add_f32 v[130:131], v76, off offset:512
	global_atomic_add_f32 v[130:131], v72, off offset:528
	global_atomic_add_f32 v[130:131], v77, off offset:516
	global_atomic_add_f32 v[130:131], v73, off offset:532
	global_atomic_add_f32 v[130:131], v78, off offset:520
	global_atomic_add_f32 v[130:131], v74, off offset:536
	global_atomic_add_f32 v[130:131], v79, off offset:524
	global_atomic_add_f32 v[130:131], v75, off offset:540
	v_add_u32_e32 v130, 48, v128
	v_ashrrev_i32_e32 v131, 31, v130
	v_lshl_add_u64 v[130:131], v[130:131], 0, s[78:79]
	v_lshlrev_b64 v[130:131], 12, v[130:131]
	v_lshl_add_u64 v[130:131], s[82:83], 0, v[130:131]
	v_lshl_add_u64 v[130:131], v[130:131], 0, s[10:11]
	v_lshl_add_u64 v[130:131], v[130:131], 0, v[132:133]
	global_atomic_add_f32 v[130:131], v100, off
	global_atomic_add_f32 v[130:131], v96, off offset:16
	global_atomic_add_f32 v[130:131], v101, off offset:4
	global_atomic_add_f32 v[130:131], v97, off offset:20
	global_atomic_add_f32 v[130:131], v102, off offset:8
	global_atomic_add_f32 v[130:131], v98, off offset:24
	global_atomic_add_f32 v[130:131], v103, off offset:12
	global_atomic_add_f32 v[130:131], v99, off offset:28
	global_atomic_add_f32 v[130:131], v68, off offset:512
	global_atomic_add_f32 v[130:131], v64, off offset:528
	global_atomic_add_f32 v[130:131], v69, off offset:516
	global_atomic_add_f32 v[130:131], v65, off offset:532
	global_atomic_add_f32 v[130:131], v70, off offset:520
	global_atomic_add_f32 v[130:131], v66, off offset:536
	global_atomic_add_f32 v[130:131], v71, off offset:524
	global_atomic_add_f32 v[130:131], v67, off offset:540
	v_add_u32_e32 v130, 0x80, v128
	v_ashrrev_i32_e32 v131, 31, v130
	v_lshl_add_u64 v[130:131], v[130:131], 0, s[78:79]
	v_lshlrev_b64 v[130:131], 12, v[130:131]
	v_lshl_add_u64 v[130:131], s[82:83], 0, v[130:131]
	v_lshl_add_u64 v[130:131], v[130:131], 0, s[10:11]
	v_lshl_add_u64 v[130:131], v[130:131], 0, v[132:133]
	global_atomic_add_f32 v[130:131], v60, off
	global_atomic_add_f32 v[130:131], v56, off offset:16
	global_atomic_add_f32 v[130:131], v61, off offset:4
	global_atomic_add_f32 v[130:131], v57, off offset:20
	global_atomic_add_f32 v[130:131], v62, off offset:8
	global_atomic_add_f32 v[130:131], v58, off offset:24
	global_atomic_add_f32 v[130:131], v63, off offset:12
	global_atomic_add_f32 v[130:131], v59, off offset:28
	global_atomic_add_f32 v[130:131], v28, off offset:512
	global_atomic_add_f32 v[130:131], v24, off offset:528
	global_atomic_add_f32 v[130:131], v29, off offset:516
	global_atomic_add_f32 v[130:131], v25, off offset:532
	global_atomic_add_f32 v[130:131], v30, off offset:520
	global_atomic_add_f32 v[130:131], v26, off offset:536
	global_atomic_add_f32 v[130:131], v31, off offset:524
; #define FOR_ROWS _Pragma("unroll") for (int ai = 0; ai < 2; ++ai) _Pragma("unroll") for (int m = 0; m < 4; ++m)
; __device__ __forceinline__ void epilogue(const int kind, CParams& p, const f32x4 (&acc)[2][2][4][2], const Unit& u, const int wr, const int wc, const int fr_in, const int fq_in) {
;     ...
;     case E_DOWN_HALF: {
;         FOR_ROWS { ROWDEF
; #pragma unroll
;             for (int bj = 0; bj < 2; ++bj) { float* hp = p.out + row * 1024 + u.pn * 256 + bj * 128 + cw;
; #pragma unroll
;                 for (int j = 0; j < 4; ++j) { unsafeAtomicAdd(hp + j, acc[ai][bj][m][0][j]); unsafeAtomicAdd(hp + 4 + j, acc[ai][bj][m][1][j]); } } }
;     } break;
	global_atomic_add_f32 v[130:131], v27, off offset:540
	v_add_u32_e32 v130, 0x90, v128
	v_ashrrev_i32_e32 v131, 31, v130
	v_lshl_add_u64 v[130:131], v[130:131], 0, s[78:79]
	v_lshlrev_b64 v[130:131], 12, v[130:131]
	v_lshl_add_u64 v[130:131], s[82:83], 0, v[130:131]
	v_lshl_add_u64 v[130:131], v[130:131], 0, s[10:11]
	v_lshl_add_u64 v[130:131], v[130:131], 0, v[132:133]
	global_atomic_add_f32 v[130:131], v52, off
	global_atomic_add_f32 v[130:131], v48, off offset:16
	global_atomic_add_f32 v[130:131], v53, off offset:4
	global_atomic_add_f32 v[130:131], v49, off offset:20
	global_atomic_add_f32 v[130:131], v54, off offset:8
	global_atomic_add_f32 v[130:131], v50, off offset:24
	global_atomic_add_f32 v[130:131], v55, off offset:12
	global_atomic_add_f32 v[130:131], v51, off offset:28
	global_atomic_add_f32 v[130:131], v20, off offset:512
	global_atomic_add_f32 v[130:131], v16, off offset:528
	global_atomic_add_f32 v[130:131], v21, off offset:516
	global_atomic_add_f32 v[130:131], v17, off offset:532
	global_atomic_add_f32 v[130:131], v22, off offset:520
	global_atomic_add_f32 v[130:131], v18, off offset:536
	global_atomic_add_f32 v[130:131], v23, off offset:524
	global_atomic_add_f32 v[130:131], v19, off offset:540
	v_add_u32_e32 v130, 0xa0, v128
	v_ashrrev_i32_e32 v131, 31, v130
	v_add_u32_e32 v128, 0xb0, v128
	v_lshl_add_u64 v[130:131], v[130:131], 0, s[78:79]
	v_ashrrev_i32_e32 v129, 31, v128
	v_lshlrev_b64 v[130:131], 12, v[130:131]
	v_lshl_add_u64 v[128:129], v[128:129], 0, s[78:79]
	v_lshl_add_u64 v[130:131], s[82:83], 0, v[130:131]
	v_lshlrev_b64 v[128:129], 12, v[128:129]
	v_lshl_add_u64 v[130:131], v[130:131], 0, s[10:11]
	v_lshl_add_u64 v[128:129], s[82:83], 0, v[128:129]
	v_lshl_add_u64 v[130:131], v[130:131], 0, v[132:133]
	v_lshl_add_u64 v[128:129], v[128:129], 0, s[10:11]
	global_atomic_add_f32 v[130:131], v44, off
	global_atomic_add_f32 v[130:131], v40, off offset:16
	global_atomic_add_f32 v[130:131], v45, off offset:4
	global_atomic_add_f32 v[130:131], v41, off offset:20
	global_atomic_add_f32 v[130:131], v46, off offset:8
	global_atomic_add_f32 v[130:131], v42, off offset:24
	global_atomic_add_f32 v[130:131], v47, off offset:12
	global_atomic_add_f32 v[130:131], v43, off offset:28
	global_atomic_add_f32 v[130:131], v12, off offset:512
	global_atomic_add_f32 v[130:131], v8, off offset:528
	global_atomic_add_f32 v[130:131], v13, off offset:516
	global_atomic_add_f32 v[130:131], v9, off offset:532
	global_atomic_add_f32 v[130:131], v14, off offset:520
	global_atomic_add_f32 v[130:131], v10, off offset:536
	global_atomic_add_f32 v[130:131], v15, off offset:524
	global_atomic_add_f32 v[130:131], v11, off offset:540
	v_lshl_add_u64 v[128:129], v[128:129], 0, v[132:133]
	global_atomic_add_f32 v[128:129], v36, off
	global_atomic_add_f32 v[128:129], v32, off offset:16
	global_atomic_add_f32 v[128:129], v37, off offset:4
	global_atomic_add_f32 v[128:129], v33, off offset:20
	global_atomic_add_f32 v[128:129], v38, off offset:8
	global_atomic_add_f32 v[128:129], v34, off offset:24
	global_atomic_add_f32 v[128:129], v39, off offset:12
	global_atomic_add_f32 v[128:129], v35, off offset:28
	global_atomic_add_f32 v[128:129], v4, off offset:512
	global_atomic_add_f32 v[128:129], v0, off offset:528
	global_atomic_add_f32 v[128:129], v5, off offset:516
	global_atomic_add_f32 v[128:129], v1, off offset:532
	global_atomic_add_f32 v[128:129], v6, off offset:520
	global_atomic_add_f32 v[128:129], v2, off offset:536
	global_atomic_add_f32 v[128:129], v7, off offset:524
	global_atomic_add_f32 v[128:129], v3, off offset:540

; __device__ __forceinline__ u32x4 pack8(f32x4 a, f32x4 b) { u32x4 w; w.x = pk2(a[0], a[1]); w.y = pk2(a[2], a[3]); w.z = pk2(b[0], b[1]); w.w = pk2(b[2], b[3]); return w; }
; #define NTL(T, ptr) __builtin_nontemporal_load((const T*)(ptr))
; __device__ __forceinline__ void epilogue(const int kind, CParams& p, const f32x4 (&acc)[2][2][4][2], const Unit& u, const int wr, const int wc, const int fr_in, const int fq_in) {
;     ...
;     case E_OUT: case E_OX: case E_DOWN: {
;         float* ss = kind == E_OUT ? p.ss1 : (kind == E_OX ? p.ss2 : p.ss3);
; #pragma unroll
;         for (int ai = 0; ai < 2; ++ai)
; #pragma unroll
;         for (int mh = 0; mh < 2; ++mh) {
;             f32x4 rv[2][2][2];
; #pragma unroll
;             for (int mm = 0; mm < 2; ++mm) { const int m = mh * 2 + mm; ROWDEF
;                 const float* rp = (kind == E_OUT) ? (row < (size_t)MP ? p.in[I_XP] + row * 1024 : p.in[I_XS] + (row - MP) * 1024) : p.out + row * 1024;
; #pragma unroll
;                 for (int bj = 0; bj < 2; ++bj) { const int col = u.pn * 256 + bj * 128 + cw; rv[mm][bj][0] = NTL(f32x4, rp + col); rv[mm][bj][1] = NTL(f32x4, rp + col + 4); } }
; #pragma unroll
;             for (int mm = 0; mm < 2; ++mm) { const int m = mh * 2 + mm; ROWDEF
;                 float s = 0.f;
; #pragma unroll
;                 for (int bj = 0; bj < 2; ++bj) {
;                     const int col = u.pn * 256 + bj * 128 + cw;
;                     const f32x4 h0 = rv[mm][bj][0] + acc[ai][bj][m][0], h1 = rv[mm][bj][1] + acc[ai][bj][m][1];
;                     *(f32x4*)(p.out + row * 1024 + col) = h0; *(f32x4*)(p.out + row * 1024 + col + 4) = h1;
;                     if (kind != E_DOWN) *(u32x4*)(p.hb + row * 1024 + col) = pack8(h0, h1);
;                     s += dot4(h0, h0) + dot4(h1, h1);
;                 }
;                 if (kind != E_DOWN) { s += __shfl_xor(s, 16); s += __shfl_xor(s, 32); if (fq == 0) unsafeAtomicAdd(ss + row, s); }
;             }
;         }
.Lmy_down:
	v_readlane_b32 s12, v245, 55
	v_readlane_b32 s13, v245, 56
	v_lshl_add_u32 v220, v216, 3, s31
	v_add_u32_e32 v224, s0, v215
	s_cmp_lt_u32 s78, 0x4000
	s_movk_i32 s1, 0x1a8
	s_cselect_b32 s1, 0x1b8, s1
	s_and_b32 s79, s78, 0x3fff
	s_load_dwordx2 s[14:15], s[12:13], 0x138
	s_load_dwordx2 s[16:17], s[12:13], s1
	s_load_dwordx2 s[10:11], s[12:13], 0x130
	v_add_u32_e32 v225, s79, v224
	v_lshlrev_b32_e32 v225, 3, v225
	v_add_u32_e32 v224, s78, v224
	v_lshlrev_b32_e32 v217, 12, v224
	s_lshl_b32 s1, s92, 10
	v_lshl_add_u32 v242, v220, 2, s1
	v_add_u32_e32 v217, v217, v242
	v_mbcnt_lo_u32_b32 v223, -1, 0
	v_mbcnt_hi_u32_b32 v223, -1, v223
	v_xor_b32_e32 v221, 16, v223
	v_xor_b32_e32 v222, 32, v223
	v_and_b32_e32 v243, 15, v223
	v_lshlrev_b32_e32 v221, 2, v221
	v_lshlrev_b32_e32 v222, 2, v222
	v_lshlrev_b32_e32 v243, 2, v243
	s_waitcnt lgkmcnt(0)
	v_mov_b32_e32 v218, v217
	global_load_dwordx4 v[128:131], v218, s[14:15] offset:0 nt
	global_load_dwordx4 v[132:135], v218, s[14:15] offset:16 nt
	global_load_dwordx4 v[136:139], v218, s[14:15] offset:512 nt
	global_load_dwordx4 v[140:143], v218, s[14:15] offset:528 nt
	v_add_u32_e32 v219, 0x10000, v217
	global_load_dwordx4 v[144:147], v219, s[14:15] offset:0 nt
	global_load_dwordx4 v[148:151], v219, s[14:15] offset:16 nt
	global_load_dwordx4 v[152:155], v219, s[14:15] offset:512 nt
	global_load_dwordx4 v[156:159], v219, s[14:15] offset:528 nt
	s_waitcnt vmcnt(4)
	v_pk_add_f32 v[124:125], v[128:129], v[124:125]
	v_pk_add_f32 v[126:127], v[130:131], v[126:127]
	v_pk_add_f32 v[120:121], v[132:133], v[120:121]
	v_pk_add_f32 v[122:123], v[134:135], v[122:123]
	v_pk_add_f32 v[92:93], v[136:137], v[92:93]
	v_pk_add_f32 v[94:95], v[138:139], v[94:95]
	v_pk_add_f32 v[88:89], v[140:141], v[88:89]
	v_pk_add_f32 v[90:91], v[142:143], v[90:91]
	v_pk_mul_f32 v[188:189], v[124:125], v[124:125]
	v_pk_mul_f32 v[190:191], v[126:127], v[126:127]
	v_pk_fma_f32 v[188:189], v[120:121], v[120:121], v[188:189]
	v_pk_fma_f32 v[190:191], v[122:123], v[122:123], v[190:191]
	v_pk_fma_f32 v[188:189], v[92:93], v[92:93], v[188:189]
	v_pk_fma_f32 v[190:191], v[94:95], v[94:95], v[190:191]
	v_pk_fma_f32 v[188:189], v[88:89], v[88:89], v[188:189]
	v_pk_fma_f32 v[190:191], v[90:91], v[90:91], v[190:191]
	s_nop 0
	v_pk_add_f32 v[188:189], v[188:189], v[190:191]
	v_add_u32_e32 v218, 0x20000, v217
	global_load_dwordx4 v[128:131], v218, s[14:15] offset:0 nt
	global_load_dwordx4 v[132:135], v218, s[14:15] offset:16 nt
	global_load_dwordx4 v[136:139], v218, s[14:15] offset:512 nt
	global_load_dwordx4 v[140:143], v218, s[14:15] offset:528 nt
	v_add_f32_e32 v172, v188, v189
	s_waitcnt vmcnt(4)
	v_pk_add_f32 v[116:117], v[144:145], v[116:117]
	v_pk_add_f32 v[118:119], v[146:147], v[118:119]
	v_pk_add_f32 v[112:113], v[148:149], v[112:113]
	v_pk_add_f32 v[114:115], v[150:151], v[114:115]
	v_pk_add_f32 v[84:85], v[152:153], v[84:85]
	v_pk_add_f32 v[86:87], v[154:155], v[86:87]
	v_pk_add_f32 v[80:81], v[156:157], v[80:81]
	v_pk_add_f32 v[82:83], v[158:159], v[82:83]
	v_pk_mul_f32 v[188:189], v[116:117], v[116:117]
	v_pk_mul_f32 v[190:191], v[118:119], v[118:119]
	v_pk_fma_f32 v[188:189], v[112:113], v[112:113], v[188:189]
	v_pk_fma_f32 v[190:191], v[114:115], v[114:115], v[190:191]
	v_pk_fma_f32 v[188:189], v[84:85], v[84:85], v[188:189]
	v_pk_fma_f32 v[190:191], v[86:87], v[86:87], v[190:191]
	v_pk_fma_f32 v[188:189], v[80:81], v[80:81], v[188:189]
	v_pk_fma_f32 v[190:191], v[82:83], v[82:83], v[190:191]
	s_nop 0
	v_pk_add_f32 v[188:189], v[188:189], v[190:191]
	v_add_u32_e32 v219, 0x30000, v217
	global_load_dwordx4 v[144:147], v219, s[14:15] offset:0 nt
	global_load_dwordx4 v[148:151], v219, s[14:15] offset:16 nt
	global_load_dwordx4 v[152:155], v219, s[14:15] offset:512 nt
	global_load_dwordx4 v[156:159], v219, s[14:15] offset:528 nt
	v_add_f32_e32 v173, v188, v189
	s_waitcnt vmcnt(4)
	v_pk_add_f32 v[108:109], v[128:129], v[108:109]
	v_pk_add_f32 v[110:111], v[130:131], v[110:111]
	v_pk_add_f32 v[104:105], v[132:133], v[104:105]
	v_pk_add_f32 v[106:107], v[134:135], v[106:107]
	v_pk_add_f32 v[76:77], v[136:137], v[76:77]
	v_pk_add_f32 v[78:79], v[138:139], v[78:79]
	v_pk_add_f32 v[72:73], v[140:141], v[72:73]
	v_pk_add_f32 v[74:75], v[142:143], v[74:75]
	v_pk_mul_f32 v[188:189], v[108:109], v[108:109]
	v_pk_mul_f32 v[190:191], v[110:111], v[110:111]
	v_pk_fma_f32 v[188:189], v[104:105], v[104:105], v[188:189]
	v_pk_fma_f32 v[190:191], v[106:107], v[106:107], v[190:191]
	v_pk_fma_f32 v[188:189], v[76:77], v[76:77], v[188:189]
	v_pk_fma_f32 v[190:191], v[78:79], v[78:79], v[190:191]
	v_pk_fma_f32 v[188:189], v[72:73], v[72:73], v[188:189]
	v_pk_fma_f32 v[190:191], v[74:75], v[74:75], v[190:191]
	s_nop 0
	v_pk_add_f32 v[188:189], v[188:189], v[190:191]
	v_add_u32_e32 v218, 0x80000, v217
	global_load_dwordx4 v[128:131], v218, s[14:15] offset:0 nt
	global_load_dwordx4 v[132:135], v218, s[14:15] offset:16 nt
	global_load_dwordx4 v[136:139], v218, s[14:15] offset:512 nt
	global_load_dwordx4 v[140:143], v218, s[14:15] offset:528 nt
	v_add_f32_e32 v174, v188, v189
	s_waitcnt vmcnt(4)
; __device__ __forceinline__ u32x4 pack8(f32x4 a, f32x4 b) { u32x4 w; w.x = pk2(a[0], a[1]); w.y = pk2(a[2], a[3]); w.z = pk2(b[0], b[1]); w.w = pk2(b[2], b[3]); return w; }
; #define NTL(T, ptr) __builtin_nontemporal_load((const T*)(ptr))
; __device__ __forceinline__ void epilogue(const int kind, CParams& p, const f32x4 (&acc)[2][2][4][2], const Unit& u, const int wr, const int wc, const int fr_in, const int fq_in) {
;     ...
;     case E_OUT: case E_OX: case E_DOWN: {
;         float* ss = kind == E_OUT ? p.ss1 : (kind == E_OX ? p.ss2 : p.ss3);
; #pragma unroll
;         for (int ai = 0; ai < 2; ++ai)
; #pragma unroll
;         for (int mh = 0; mh < 2; ++mh) {
;             f32x4 rv[2][2][2];
; #pragma unroll
;             for (int mm = 0; mm < 2; ++mm) { const int m = mh * 2 + mm; ROWDEF
;                 const float* rp = (kind == E_OUT) ? (row < (size_t)MP ? p.in[I_XP] + row * 1024 : p.in[I_XS] + (row - MP) * 1024) : p.out + row * 1024;
; #pragma unroll
;                 for (int bj = 0; bj < 2; ++bj) { const int col = u.pn * 256 + bj * 128 + cw; rv[mm][bj][0] = NTL(f32x4, rp + col); rv[mm][bj][1] = NTL(f32x4, rp + col + 4); } }
; #pragma unroll
;             for (int mm = 0; mm < 2; ++mm) { const int m = mh * 2 + mm; ROWDEF
;                 float s = 0.f;
; #pragma unroll
;                 for (int bj = 0; bj < 2; ++bj) {
;                     const int col = u.pn * 256 + bj * 128 + cw;
;                     const f32x4 h0 = rv[mm][bj][0] + acc[ai][bj][m][0], h1 = rv[mm][bj][1] + acc[ai][bj][m][1];
;                     *(f32x4*)(p.out + row * 1024 + col) = h0; *(f32x4*)(p.out + row * 1024 + col + 4) = h1;
;                     if (kind != E_DOWN) *(u32x4*)(p.hb + row * 1024 + col) = pack8(h0, h1);
;                     s += dot4(h0, h0) + dot4(h1, h1);
;                 }
;                 if (kind != E_DOWN) { s += __shfl_xor(s, 16); s += __shfl_xor(s, 32); if (fq == 0) unsafeAtomicAdd(ss + row, s); }
;             }
;         }
	v_pk_add_f32 v[100:101], v[144:145], v[100:101]
	v_pk_add_f32 v[102:103], v[146:147], v[102:103]
	v_pk_add_f32 v[96:97], v[148:149], v[96:97]
	v_pk_add_f32 v[98:99], v[150:151], v[98:99]
	v_pk_add_f32 v[68:69], v[152:153], v[68:69]
	v_pk_add_f32 v[70:71], v[154:155], v[70:71]
	v_pk_add_f32 v[64:65], v[156:157], v[64:65]
	v_pk_add_f32 v[66:67], v[158:159], v[66:67]
	v_pk_mul_f32 v[188:189], v[100:101], v[100:101]
	v_pk_mul_f32 v[190:191], v[102:103], v[102:103]
	v_pk_fma_f32 v[188:189], v[96:97], v[96:97], v[188:189]
	v_pk_fma_f32 v[190:191], v[98:99], v[98:99], v[190:191]
	v_pk_fma_f32 v[188:189], v[68:69], v[68:69], v[188:189]
	v_pk_fma_f32 v[190:191], v[70:71], v[70:71], v[190:191]
	v_pk_fma_f32 v[188:189], v[64:65], v[64:65], v[188:189]
	v_pk_fma_f32 v[190:191], v[66:67], v[66:67], v[190:191]
	s_nop 0
	v_pk_add_f32 v[188:189], v[188:189], v[190:191]
	v_add_u32_e32 v219, 0x90000, v217
	global_load_dwordx4 v[144:147], v219, s[14:15] offset:0 nt
	global_load_dwordx4 v[148:151], v219, s[14:15] offset:16 nt
	global_load_dwordx4 v[152:155], v219, s[14:15] offset:512 nt
	global_load_dwordx4 v[156:159], v219, s[14:15] offset:528 nt
	v_add_f32_e32 v175, v188, v189
	s_waitcnt vmcnt(4)
	v_pk_add_f32 v[60:61], v[128:129], v[60:61]
	v_pk_add_f32 v[62:63], v[130:131], v[62:63]
	v_pk_add_f32 v[56:57], v[132:133], v[56:57]
	v_pk_add_f32 v[58:59], v[134:135], v[58:59]
	v_pk_add_f32 v[28:29], v[136:137], v[28:29]
	v_pk_add_f32 v[30:31], v[138:139], v[30:31]
	v_pk_add_f32 v[24:25], v[140:141], v[24:25]
	v_pk_add_f32 v[26:27], v[142:143], v[26:27]
	v_pk_mul_f32 v[188:189], v[60:61], v[60:61]
	v_pk_mul_f32 v[190:191], v[62:63], v[62:63]
	v_pk_fma_f32 v[188:189], v[56:57], v[56:57], v[188:189]
	v_pk_fma_f32 v[190:191], v[58:59], v[58:59], v[190:191]
	v_pk_fma_f32 v[188:189], v[28:29], v[28:29], v[188:189]
	v_pk_fma_f32 v[190:191], v[30:31], v[30:31], v[190:191]
	v_pk_fma_f32 v[188:189], v[24:25], v[24:25], v[188:189]
	v_pk_fma_f32 v[190:191], v[26:27], v[26:27], v[190:191]
	s_nop 0
	v_pk_add_f32 v[188:189], v[188:189], v[190:191]
	v_add_u32_e32 v218, 0xa0000, v217
	global_load_dwordx4 v[128:131], v218, s[14:15] offset:0 nt
	global_load_dwordx4 v[132:135], v218, s[14:15] offset:16 nt
	global_load_dwordx4 v[136:139], v218, s[14:15] offset:512 nt
	global_load_dwordx4 v[140:143], v218, s[14:15] offset:528 nt
	v_add_f32_e32 v176, v188, v189
	s_waitcnt vmcnt(4)
	v_pk_add_f32 v[52:53], v[144:145], v[52:53]
	v_pk_add_f32 v[54:55], v[146:147], v[54:55]
	v_pk_add_f32 v[48:49], v[148:149], v[48:49]
	v_pk_add_f32 v[50:51], v[150:151], v[50:51]
	v_pk_add_f32 v[20:21], v[152:153], v[20:21]
	v_pk_add_f32 v[22:23], v[154:155], v[22:23]
	v_pk_add_f32 v[16:17], v[156:157], v[16:17]
	v_pk_add_f32 v[18:19], v[158:159], v[18:19]
	v_pk_mul_f32 v[188:189], v[52:53], v[52:53]
	v_pk_mul_f32 v[190:191], v[54:55], v[54:55]
	v_pk_fma_f32 v[188:189], v[48:49], v[48:49], v[188:189]
	v_pk_fma_f32 v[190:191], v[50:51], v[50:51], v[190:191]
	v_pk_fma_f32 v[188:189], v[20:21], v[20:21], v[188:189]
	v_pk_fma_f32 v[190:191], v[22:23], v[22:23], v[190:191]
	v_pk_fma_f32 v[188:189], v[16:17], v[16:17], v[188:189]
	v_pk_fma_f32 v[190:191], v[18:19], v[18:19], v[190:191]
	s_nop 0
	v_pk_add_f32 v[188:189], v[188:189], v[190:191]
	v_add_u32_e32 v219, 0xb0000, v217
	global_load_dwordx4 v[144:147], v219, s[14:15] offset:0 nt
	global_load_dwordx4 v[148:151], v219, s[14:15] offset:16 nt
	global_load_dwordx4 v[152:155], v219, s[14:15] offset:512 nt
	global_load_dwordx4 v[156:159], v219, s[14:15] offset:528 nt
	v_add_f32_e32 v177, v188, v189
	s_waitcnt vmcnt(4)
	v_pk_add_f32 v[44:45], v[128:129], v[44:45]
	v_pk_add_f32 v[46:47], v[130:131], v[46:47]
	v_pk_add_f32 v[40:41], v[132:133], v[40:41]
	v_pk_add_f32 v[42:43], v[134:135], v[42:43]
	v_pk_add_f32 v[12:13], v[136:137], v[12:13]
	v_pk_add_f32 v[14:15], v[138:139], v[14:15]
	v_pk_add_f32 v[8:9], v[140:141], v[8:9]
	v_pk_add_f32 v[10:11], v[142:143], v[10:11]
	v_pk_mul_f32 v[188:189], v[44:45], v[44:45]
	v_pk_mul_f32 v[190:191], v[46:47], v[46:47]
	v_pk_fma_f32 v[188:189], v[40:41], v[40:41], v[188:189]
	v_pk_fma_f32 v[190:191], v[42:43], v[42:43], v[190:191]
	v_pk_fma_f32 v[188:189], v[12:13], v[12:13], v[188:189]
	v_pk_fma_f32 v[190:191], v[14:15], v[14:15], v[190:191]
	v_pk_fma_f32 v[188:189], v[8:9], v[8:9], v[188:189]
	v_pk_fma_f32 v[190:191], v[10:11], v[10:11], v[190:191]
	s_nop 0
	v_pk_add_f32 v[188:189], v[188:189], v[190:191]
	s_nop 1
	v_add_f32_e32 v178, v188, v189
	s_waitcnt vmcnt(0)
	v_pk_add_f32 v[36:37], v[144:145], v[36:37]
	v_pk_add_f32 v[38:39], v[146:147], v[38:39]
	v_pk_add_f32 v[32:33], v[148:149], v[32:33]
	v_pk_add_f32 v[34:35], v[150:151], v[34:35]
	v_pk_add_f32 v[4:5], v[152:153], v[4:5]
	v_pk_add_f32 v[6:7], v[154:155], v[6:7]
	v_pk_add_f32 v[0:1], v[156:157], v[0:1]
	v_pk_add_f32 v[2:3], v[158:159], v[2:3]
	v_pk_mul_f32 v[188:189], v[36:37], v[36:37]
	v_pk_mul_f32 v[190:191], v[38:39], v[38:39]
	v_pk_fma_f32 v[188:189], v[32:33], v[32:33], v[188:189]
	v_pk_fma_f32 v[190:191], v[34:35], v[34:35], v[190:191]
	v_pk_fma_f32 v[188:189], v[4:5], v[4:5], v[188:189]
	v_pk_fma_f32 v[190:191], v[6:7], v[6:7], v[190:191]
	v_pk_fma_f32 v[188:189], v[0:1], v[0:1], v[188:189]
	v_pk_fma_f32 v[190:191], v[2:3], v[2:3], v[190:191]
	s_nop 0
	v_pk_add_f32 v[188:189], v[188:189], v[190:191]
	s_nop 1
	v_add_f32_e32 v179, v188, v189
	ds_bpermute_b32 v180, v221, v172
	ds_bpermute_b32 v181, v221, v173
	ds_bpermute_b32 v182, v221, v174
	ds_bpermute_b32 v183, v221, v175
	ds_bpermute_b32 v184, v221, v176
	ds_bpermute_b32 v185, v221, v177
	ds_bpermute_b32 v186, v221, v178
	ds_bpermute_b32 v187, v221, v179
	s_waitcnt lgkmcnt(7)
; __device__ __forceinline__ u32x4 pack8(f32x4 a, f32x4 b) { u32x4 w; w.x = pk2(a[0], a[1]); w.y = pk2(a[2], a[3]); w.z = pk2(b[0], b[1]); w.w = pk2(b[2], b[3]); return w; }
; #define NTL(T, ptr) __builtin_nontemporal_load((const T*)(ptr))
; __device__ __forceinline__ void epilogue(const int kind, CParams& p, const f32x4 (&acc)[2][2][4][2], const Unit& u, const int wr, const int wc, const int fr_in, const int fq_in) {
;     ...
;     case E_OUT: case E_OX: case E_DOWN: {
;         float* ss = kind == E_OUT ? p.ss1 : (kind == E_OX ? p.ss2 : p.ss3);
; #pragma unroll
;         for (int ai = 0; ai < 2; ++ai)
; #pragma unroll
;         for (int mh = 0; mh < 2; ++mh) {
;             f32x4 rv[2][2][2];
; #pragma unroll
;             for (int mm = 0; mm < 2; ++mm) { const int m = mh * 2 + mm; ROWDEF
;                 const float* rp = (kind == E_OUT) ? (row < (size_t)MP ? p.in[I_XP] + row * 1024 : p.in[I_XS] + (row - MP) * 1024) : p.out + row * 1024;
; #pragma unroll
;                 for (int bj = 0; bj < 2; ++bj) { const int col = u.pn * 256 + bj * 128 + cw; rv[mm][bj][0] = NTL(f32x4, rp + col); rv[mm][bj][1] = NTL(f32x4, rp + col + 4); } }
; #pragma unroll
;             for (int mm = 0; mm < 2; ++mm) { const int m = mh * 2 + mm; ROWDEF
;                 float s = 0.f;
; #pragma unroll
;                 for (int bj = 0; bj < 2; ++bj) {
;                     const int col = u.pn * 256 + bj * 128 + cw;
;                     const f32x4 h0 = rv[mm][bj][0] + acc[ai][bj][m][0], h1 = rv[mm][bj][1] + acc[ai][bj][m][1];
;                     *(f32x4*)(p.out + row * 1024 + col) = h0; *(f32x4*)(p.out + row * 1024 + col + 4) = h1;
;                     if (kind != E_DOWN) *(u32x4*)(p.hb + row * 1024 + col) = pack8(h0, h1);
;                     s += dot4(h0, h0) + dot4(h1, h1);
;                 }
;                 if (kind != E_DOWN) { s += __shfl_xor(s, 16); s += __shfl_xor(s, 32); if (fq == 0) unsafeAtomicAdd(ss + row, s); }
;             }
;         }
; __device__ __forceinline__ void phase_final(CParams& p) {
;     ...
;             if (row < M) { const float rs = rsqrtf(sv[b] * (1.f / 1024.f) + 1e-6f);
	v_add_f32_e32 v172, v172, v180
	s_waitcnt lgkmcnt(6)
	v_add_f32_e32 v173, v173, v181
	s_waitcnt lgkmcnt(5)
	v_add_f32_e32 v174, v174, v182
	s_waitcnt lgkmcnt(4)
	v_add_f32_e32 v175, v175, v183
	s_waitcnt lgkmcnt(3)
	v_add_f32_e32 v176, v176, v184
	s_waitcnt lgkmcnt(2)
	v_add_f32_e32 v177, v177, v185
	s_waitcnt lgkmcnt(1)
	v_add_f32_e32 v178, v178, v186
	s_waitcnt lgkmcnt(0)
	v_add_f32_e32 v179, v179, v187
	ds_bpermute_b32 v180, v222, v172
	ds_bpermute_b32 v181, v222, v173
	ds_bpermute_b32 v182, v222, v174
	ds_bpermute_b32 v183, v222, v175
	ds_bpermute_b32 v184, v222, v176
	ds_bpermute_b32 v185, v222, v177
	ds_bpermute_b32 v186, v222, v178
	ds_bpermute_b32 v187, v222, v179
	s_waitcnt lgkmcnt(7)
	v_add_f32_e32 v172, v172, v180
	s_waitcnt lgkmcnt(6)
	v_add_f32_e32 v173, v173, v181
	s_waitcnt lgkmcnt(5)
	v_add_f32_e32 v174, v174, v182
	s_waitcnt lgkmcnt(4)
	v_add_f32_e32 v175, v175, v183
	s_waitcnt lgkmcnt(3)
	v_add_f32_e32 v176, v176, v184
	s_waitcnt lgkmcnt(2)
	v_add_f32_e32 v177, v177, v185
	s_waitcnt lgkmcnt(1)
	v_add_f32_e32 v178, v178, v186
	s_waitcnt lgkmcnt(0)
	v_add_f32_e32 v179, v179, v187
	global_load_dwordx4 v[226:229], v242, s[10:11] offset:0
	global_load_dwordx4 v[230:233], v242, s[10:11] offset:16
	global_load_dwordx4 v[234:237], v242, s[10:11] offset:512
	global_load_dwordx4 v[238:241], v242, s[10:11] offset:528
	v_mov_b32_e32 v188, 0
	v_mov_b32_e32 v189, 0x41d00000
	v_mov_b32_e32 v190, 0
	v_mov_b32_e32 v191, 0xc2100000
	v_cvt_f64_f32_e32 v[128:129], v172
	v_cvt_f64_f32_e32 v[130:131], v173
	v_cvt_f64_f32_e32 v[132:133], v174
	v_cvt_f64_f32_e32 v[134:135], v175
	v_cvt_f64_f32_e32 v[136:137], v176
	v_cvt_f64_f32_e32 v[138:139], v177
	v_cvt_f64_f32_e32 v[140:141], v178
	v_cvt_f64_f32_e32 v[142:143], v179
	s_nop 1
	v_add_f64 v[128:129], v[128:129], v[188:189]
	v_add_f64 v[130:131], v[130:131], v[188:189]
	v_add_f64 v[132:133], v[132:133], v[188:189]
	v_add_f64 v[134:135], v[134:135], v[188:189]
	v_add_f64 v[136:137], v[136:137], v[188:189]
	v_add_f64 v[138:139], v[138:139], v[188:189]
	v_add_f64 v[140:141], v[140:141], v[188:189]
	v_add_f64 v[142:143], v[142:143], v[188:189]
	s_mov_b64 exec, 0xffff
	global_atomic_add_f64 v225, v[128:129], s[16:17] offset:0
	global_atomic_add_f64 v225, v[130:131], s[16:17] offset:128
	global_atomic_add_f64 v225, v[132:133], s[16:17] offset:256
	global_atomic_add_f64 v225, v[134:135], s[16:17] offset:384
	global_atomic_add_f64 v225, v[136:137], s[16:17] offset:1024
	global_atomic_add_f64 v225, v[138:139], s[16:17] offset:1152
	global_atomic_add_f64 v225, v[140:141], s[16:17] offset:1280
	global_atomic_add_f64 v225, v[142:143], s[16:17] offset:1408
	s_mov_b32 s1, 0
.Ldn_spin:
	v_mov_b64_e32 v[144:145], 0
	v_mov_b64_e32 v[146:147], 0
	v_mov_b64_e32 v[148:149], 0
	v_mov_b64_e32 v[150:151], 0
	v_mov_b64_e32 v[152:153], 0
	v_mov_b64_e32 v[154:155], 0
	v_mov_b64_e32 v[156:157], 0
	v_mov_b64_e32 v[158:159], 0
	global_atomic_add_f64 v[144:145], v225, v[144:145], s[16:17] offset:0 sc0
	global_atomic_add_f64 v[146:147], v225, v[146:147], s[16:17] offset:128 sc0
	global_atomic_add_f64 v[148:149], v225, v[148:149], s[16:17] offset:256 sc0
	global_atomic_add_f64 v[150:151], v225, v[150:151], s[16:17] offset:384 sc0
	global_atomic_add_f64 v[152:153], v225, v[152:153], s[16:17] offset:1024 sc0
	global_atomic_add_f64 v[154:155], v225, v[154:155], s[16:17] offset:1152 sc0
	global_atomic_add_f64 v[156:157], v225, v[156:157], s[16:17] offset:1280 sc0
	global_atomic_add_f64 v[158:159], v225, v[158:159], s[16:17] offset:1408 sc0
	s_waitcnt vmcnt(0)
	v_min_u32_e32 v220, v145, v147
	v_min_u32_e32 v220, v220, v149
	v_min_u32_e32 v220, v220, v151
	v_min_u32_e32 v220, v220, v153
	v_min_u32_e32 v220, v220, v155
	v_min_u32_e32 v220, v220, v157
	v_min_u32_e32 v220, v220, v159
	v_cmp_gt_u32_e32 vcc, 0x42100000, v220
	s_cbranch_vccz .Ldn_done
	s_sleep 1
	s_add_u32 s1, s1, 1
	s_cmp_lt_u32 s1, 0x4000
	s_cbranch_scc1 .Ldn_spin
.Ldn_done:
	v_add_f64 v[144:145], v[144:145], v[190:191]
	v_add_f64 v[146:147], v[146:147], v[190:191]
	v_add_f64 v[148:149], v[148:149], v[190:191]
	v_add_f64 v[150:151], v[150:151], v[190:191]
	v_add_f64 v[152:153], v[152:153], v[190:191]
	v_add_f64 v[154:155], v[154:155], v[190:191]
	v_add_f64 v[156:157], v[156:157], v[190:191]
	v_add_f64 v[158:159], v[158:159], v[190:191]
	s_nop 1
	v_cvt_f32_f64_e32 v180, v[144:145]
	v_cvt_f32_f64_e32 v181, v[146:147]
	v_cvt_f32_f64_e32 v182, v[148:149]
	v_cvt_f32_f64_e32 v183, v[150:151]
	v_cvt_f32_f64_e32 v184, v[152:153]
	v_cvt_f32_f64_e32 v185, v[154:155]
	v_cvt_f32_f64_e32 v186, v[156:157]
	v_cvt_f32_f64_e32 v187, v[158:159]
	s_nop 1
	v_fmamk_f32 v180, v180, 0x3a800000, v193
	v_fmamk_f32 v181, v181, 0x3a800000, v193
	v_fmamk_f32 v182, v182, 0x3a800000, v193
	v_fmamk_f32 v183, v183, 0x3a800000, v193
	v_fmamk_f32 v184, v184, 0x3a800000, v193
	v_fmamk_f32 v185, v185, 0x3a800000, v193
	v_fmamk_f32 v186, v186, 0x3a800000, v193
	v_fmamk_f32 v187, v187, 0x3a800000, v193
	v_rsq_f32_e32 v180, v180
	v_rsq_f32_e32 v181, v181
	v_rsq_f32_e32 v182, v182
	v_rsq_f32_e32 v183, v183
	v_rsq_f32_e32 v184, v184
	v_rsq_f32_e32 v185, v185
	v_rsq_f32_e32 v186, v186
	v_rsq_f32_e32 v187, v187
	s_mov_b64 exec, -1
	s_nop 1
	ds_bpermute_b32 v180, v243, v180
	ds_bpermute_b32 v181, v243, v181
	ds_bpermute_b32 v182, v243, v182
	ds_bpermute_b32 v183, v243, v183
	ds_bpermute_b32 v184, v243, v184
	ds_bpermute_b32 v185, v243, v185
	ds_bpermute_b32 v186, v243, v186
	ds_bpermute_b32 v187, v243, v187
	v_mov_b32_e32 v218, v217
	s_waitcnt lgkmcnt(7)
	s_waitcnt lgkmcnt(6)
; __device__ __forceinline__ void phase_final(CParams& p) {
;     ...
;             if (row < M) { const float rs = rsqrtf(sv[b] * (1.f / 1024.f) + 1e-6f);
; #pragma unroll
;                 for (int i = 0; i < 4; ++i) __builtin_nontemporal_store(v[b][i] * rs * gfin[i], (f32x4*)(p.out + (size_t)row * 1024 + lane * 4 + i * 256)); } }
	v_pk_mul_f32 v[124:125], v[124:125], v[180:181] op_sel_hi:[1,0]
	v_pk_mul_f32 v[126:127], v[126:127], v[180:181] op_sel_hi:[1,0]
	v_pk_mul_f32 v[120:121], v[120:121], v[180:181] op_sel_hi:[1,0]
	v_pk_mul_f32 v[122:123], v[122:123], v[180:181] op_sel_hi:[1,0]
	v_pk_mul_f32 v[92:93], v[92:93], v[180:181] op_sel_hi:[1,0]
	v_pk_mul_f32 v[94:95], v[94:95], v[180:181] op_sel_hi:[1,0]
	v_pk_mul_f32 v[88:89], v[88:89], v[180:181] op_sel_hi:[1,0]
	v_pk_mul_f32 v[90:91], v[90:91], v[180:181] op_sel_hi:[1,0]
	v_pk_mul_f32 v[124:125], v[124:125], v[226:227]
	v_pk_mul_f32 v[126:127], v[126:127], v[228:229]
	v_pk_mul_f32 v[120:121], v[120:121], v[230:231]
	v_pk_mul_f32 v[122:123], v[122:123], v[232:233]
	v_pk_mul_f32 v[92:93], v[92:93], v[234:235]
	v_pk_mul_f32 v[94:95], v[94:95], v[236:237]
	v_pk_mul_f32 v[88:89], v[88:89], v[238:239]
	v_pk_mul_f32 v[90:91], v[90:91], v[240:241]
	global_store_dwordx4 v218, v[124:127], s[14:15] offset:0 nt
	global_store_dwordx4 v218, v[120:123], s[14:15] offset:16 nt
	global_store_dwordx4 v218, v[92:95], s[14:15] offset:512 nt
	global_store_dwordx4 v218, v[88:91], s[14:15] offset:528 nt
	v_add_u32_e32 v219, 0x10000, v217
	s_waitcnt lgkmcnt(6)
	v_pk_mul_f32 v[116:117], v[116:117], v[180:181] op_sel:[0,1] op_sel_hi:[1,1]
	v_pk_mul_f32 v[118:119], v[118:119], v[180:181] op_sel:[0,1] op_sel_hi:[1,1]
	v_pk_mul_f32 v[112:113], v[112:113], v[180:181] op_sel:[0,1] op_sel_hi:[1,1]
	v_pk_mul_f32 v[114:115], v[114:115], v[180:181] op_sel:[0,1] op_sel_hi:[1,1]
	v_pk_mul_f32 v[84:85], v[84:85], v[180:181] op_sel:[0,1] op_sel_hi:[1,1]
	v_pk_mul_f32 v[86:87], v[86:87], v[180:181] op_sel:[0,1] op_sel_hi:[1,1]
	v_pk_mul_f32 v[80:81], v[80:81], v[180:181] op_sel:[0,1] op_sel_hi:[1,1]
	v_pk_mul_f32 v[82:83], v[82:83], v[180:181] op_sel:[0,1] op_sel_hi:[1,1]
	v_pk_mul_f32 v[116:117], v[116:117], v[226:227]
	v_pk_mul_f32 v[118:119], v[118:119], v[228:229]
	v_pk_mul_f32 v[112:113], v[112:113], v[230:231]
	v_pk_mul_f32 v[114:115], v[114:115], v[232:233]
	v_pk_mul_f32 v[84:85], v[84:85], v[234:235]
	v_pk_mul_f32 v[86:87], v[86:87], v[236:237]
	v_pk_mul_f32 v[80:81], v[80:81], v[238:239]
	v_pk_mul_f32 v[82:83], v[82:83], v[240:241]
	global_store_dwordx4 v219, v[116:119], s[14:15] offset:0 nt
	global_store_dwordx4 v219, v[112:115], s[14:15] offset:16 nt
	global_store_dwordx4 v219, v[84:87], s[14:15] offset:512 nt
	global_store_dwordx4 v219, v[80:83], s[14:15] offset:528 nt
	v_add_u32_e32 v218, 0x20000, v217
	s_waitcnt lgkmcnt(5)
	s_waitcnt lgkmcnt(4)
	v_pk_mul_f32 v[108:109], v[108:109], v[182:183] op_sel_hi:[1,0]
	v_pk_mul_f32 v[110:111], v[110:111], v[182:183] op_sel_hi:[1,0]
	v_pk_mul_f32 v[104:105], v[104:105], v[182:183] op_sel_hi:[1,0]
	v_pk_mul_f32 v[106:107], v[106:107], v[182:183] op_sel_hi:[1,0]
	v_pk_mul_f32 v[76:77], v[76:77], v[182:183] op_sel_hi:[1,0]
	v_pk_mul_f32 v[78:79], v[78:79], v[182:183] op_sel_hi:[1,0]
	v_pk_mul_f32 v[72:73], v[72:73], v[182:183] op_sel_hi:[1,0]
	v_pk_mul_f32 v[74:75], v[74:75], v[182:183] op_sel_hi:[1,0]
	v_pk_mul_f32 v[108:109], v[108:109], v[226:227]
	v_pk_mul_f32 v[110:111], v[110:111], v[228:229]
	v_pk_mul_f32 v[104:105], v[104:105], v[230:231]
	v_pk_mul_f32 v[106:107], v[106:107], v[232:233]
	v_pk_mul_f32 v[76:77], v[76:77], v[234:235]
	v_pk_mul_f32 v[78:79], v[78:79], v[236:237]
	v_pk_mul_f32 v[72:73], v[72:73], v[238:239]
	v_pk_mul_f32 v[74:75], v[74:75], v[240:241]
	global_store_dwordx4 v218, v[108:111], s[14:15] offset:0 nt
	global_store_dwordx4 v218, v[104:107], s[14:15] offset:16 nt
	global_store_dwordx4 v218, v[76:79], s[14:15] offset:512 nt
	global_store_dwordx4 v218, v[72:75], s[14:15] offset:528 nt
	v_add_u32_e32 v219, 0x30000, v217
	s_waitcnt lgkmcnt(4)
	v_pk_mul_f32 v[100:101], v[100:101], v[182:183] op_sel:[0,1] op_sel_hi:[1,1]
	v_pk_mul_f32 v[102:103], v[102:103], v[182:183] op_sel:[0,1] op_sel_hi:[1,1]
	v_pk_mul_f32 v[96:97], v[96:97], v[182:183] op_sel:[0,1] op_sel_hi:[1,1]
	v_pk_mul_f32 v[98:99], v[98:99], v[182:183] op_sel:[0,1] op_sel_hi:[1,1]
	v_pk_mul_f32 v[68:69], v[68:69], v[182:183] op_sel:[0,1] op_sel_hi:[1,1]
	v_pk_mul_f32 v[70:71], v[70:71], v[182:183] op_sel:[0,1] op_sel_hi:[1,1]
	v_pk_mul_f32 v[64:65], v[64:65], v[182:183] op_sel:[0,1] op_sel_hi:[1,1]
	v_pk_mul_f32 v[66:67], v[66:67], v[182:183] op_sel:[0,1] op_sel_hi:[1,1]
	v_pk_mul_f32 v[100:101], v[100:101], v[226:227]
	v_pk_mul_f32 v[102:103], v[102:103], v[228:229]
	v_pk_mul_f32 v[96:97], v[96:97], v[230:231]
	v_pk_mul_f32 v[98:99], v[98:99], v[232:233]
	v_pk_mul_f32 v[68:69], v[68:69], v[234:235]
	v_pk_mul_f32 v[70:71], v[70:71], v[236:237]
	v_pk_mul_f32 v[64:65], v[64:65], v[238:239]
	v_pk_mul_f32 v[66:67], v[66:67], v[240:241]
	global_store_dwordx4 v219, v[100:103], s[14:15] offset:0 nt
	global_store_dwordx4 v219, v[96:99], s[14:15] offset:16 nt
	global_store_dwordx4 v219, v[68:71], s[14:15] offset:512 nt
	global_store_dwordx4 v219, v[64:67], s[14:15] offset:528 nt
	v_add_u32_e32 v218, 0x80000, v217
	s_waitcnt lgkmcnt(3)
; __device__ __forceinline__ void phase_final(CParams& p) {
;     ...
;             if (row < M) { const float rs = rsqrtf(sv[b] * (1.f / 1024.f) + 1e-6f);
; #pragma unroll
;                 for (int i = 0; i < 4; ++i) __builtin_nontemporal_store(v[b][i] * rs * gfin[i], (f32x4*)(p.out + (size_t)row * 1024 + lane * 4 + i * 256)); } }
	s_waitcnt lgkmcnt(2)
	v_pk_mul_f32 v[60:61], v[60:61], v[184:185] op_sel_hi:[1,0]
	v_pk_mul_f32 v[62:63], v[62:63], v[184:185] op_sel_hi:[1,0]
	v_pk_mul_f32 v[56:57], v[56:57], v[184:185] op_sel_hi:[1,0]
	v_pk_mul_f32 v[58:59], v[58:59], v[184:185] op_sel_hi:[1,0]
	v_pk_mul_f32 v[28:29], v[28:29], v[184:185] op_sel_hi:[1,0]
	v_pk_mul_f32 v[30:31], v[30:31], v[184:185] op_sel_hi:[1,0]
	v_pk_mul_f32 v[24:25], v[24:25], v[184:185] op_sel_hi:[1,0]
	v_pk_mul_f32 v[26:27], v[26:27], v[184:185] op_sel_hi:[1,0]
	v_pk_mul_f32 v[60:61], v[60:61], v[226:227]
	v_pk_mul_f32 v[62:63], v[62:63], v[228:229]
	v_pk_mul_f32 v[56:57], v[56:57], v[230:231]
	v_pk_mul_f32 v[58:59], v[58:59], v[232:233]
	v_pk_mul_f32 v[28:29], v[28:29], v[234:235]
	v_pk_mul_f32 v[30:31], v[30:31], v[236:237]
	v_pk_mul_f32 v[24:25], v[24:25], v[238:239]
	v_pk_mul_f32 v[26:27], v[26:27], v[240:241]
	global_store_dwordx4 v218, v[60:63], s[14:15] offset:0 nt
	global_store_dwordx4 v218, v[56:59], s[14:15] offset:16 nt
	global_store_dwordx4 v218, v[28:31], s[14:15] offset:512 nt
	global_store_dwordx4 v218, v[24:27], s[14:15] offset:528 nt
	v_add_u32_e32 v219, 0x90000, v217
	s_waitcnt lgkmcnt(2)
	v_pk_mul_f32 v[52:53], v[52:53], v[184:185] op_sel:[0,1] op_sel_hi:[1,1]
	v_pk_mul_f32 v[54:55], v[54:55], v[184:185] op_sel:[0,1] op_sel_hi:[1,1]
	v_pk_mul_f32 v[48:49], v[48:49], v[184:185] op_sel:[0,1] op_sel_hi:[1,1]
	v_pk_mul_f32 v[50:51], v[50:51], v[184:185] op_sel:[0,1] op_sel_hi:[1,1]
	v_pk_mul_f32 v[20:21], v[20:21], v[184:185] op_sel:[0,1] op_sel_hi:[1,1]
	v_pk_mul_f32 v[22:23], v[22:23], v[184:185] op_sel:[0,1] op_sel_hi:[1,1]
	v_pk_mul_f32 v[16:17], v[16:17], v[184:185] op_sel:[0,1] op_sel_hi:[1,1]
	v_pk_mul_f32 v[18:19], v[18:19], v[184:185] op_sel:[0,1] op_sel_hi:[1,1]
	v_pk_mul_f32 v[52:53], v[52:53], v[226:227]
	v_pk_mul_f32 v[54:55], v[54:55], v[228:229]
	v_pk_mul_f32 v[48:49], v[48:49], v[230:231]
	v_pk_mul_f32 v[50:51], v[50:51], v[232:233]
	v_pk_mul_f32 v[20:21], v[20:21], v[234:235]
	v_pk_mul_f32 v[22:23], v[22:23], v[236:237]
	v_pk_mul_f32 v[16:17], v[16:17], v[238:239]
	v_pk_mul_f32 v[18:19], v[18:19], v[240:241]
	global_store_dwordx4 v219, v[52:55], s[14:15] offset:0 nt
	global_store_dwordx4 v219, v[48:51], s[14:15] offset:16 nt
	global_store_dwordx4 v219, v[20:23], s[14:15] offset:512 nt
	global_store_dwordx4 v219, v[16:19], s[14:15] offset:528 nt
	v_add_u32_e32 v218, 0xa0000, v217
	s_waitcnt lgkmcnt(1)
	s_waitcnt lgkmcnt(0)
	v_pk_mul_f32 v[44:45], v[44:45], v[186:187] op_sel_hi:[1,0]
	v_pk_mul_f32 v[46:47], v[46:47], v[186:187] op_sel_hi:[1,0]
	v_pk_mul_f32 v[40:41], v[40:41], v[186:187] op_sel_hi:[1,0]
	v_pk_mul_f32 v[42:43], v[42:43], v[186:187] op_sel_hi:[1,0]
	v_pk_mul_f32 v[12:13], v[12:13], v[186:187] op_sel_hi:[1,0]
	v_pk_mul_f32 v[14:15], v[14:15], v[186:187] op_sel_hi:[1,0]
	v_pk_mul_f32 v[8:9], v[8:9], v[186:187] op_sel_hi:[1,0]
	v_pk_mul_f32 v[10:11], v[10:11], v[186:187] op_sel_hi:[1,0]
	v_pk_mul_f32 v[44:45], v[44:45], v[226:227]
	v_pk_mul_f32 v[46:47], v[46:47], v[228:229]
	v_pk_mul_f32 v[40:41], v[40:41], v[230:231]
	v_pk_mul_f32 v[42:43], v[42:43], v[232:233]
	v_pk_mul_f32 v[12:13], v[12:13], v[234:235]
	v_pk_mul_f32 v[14:15], v[14:15], v[236:237]
	v_pk_mul_f32 v[8:9], v[8:9], v[238:239]
	v_pk_mul_f32 v[10:11], v[10:11], v[240:241]
	global_store_dwordx4 v218, v[44:47], s[14:15] offset:0 nt
	global_store_dwordx4 v218, v[40:43], s[14:15] offset:16 nt
	global_store_dwordx4 v218, v[12:15], s[14:15] offset:512 nt
	global_store_dwordx4 v218, v[8:11], s[14:15] offset:528 nt
	v_add_u32_e32 v219, 0xb0000, v217
	s_waitcnt lgkmcnt(0)
	v_pk_mul_f32 v[36:37], v[36:37], v[186:187] op_sel:[0,1] op_sel_hi:[1,1]
	v_pk_mul_f32 v[38:39], v[38:39], v[186:187] op_sel:[0,1] op_sel_hi:[1,1]
	v_pk_mul_f32 v[32:33], v[32:33], v[186:187] op_sel:[0,1] op_sel_hi:[1,1]
	v_pk_mul_f32 v[34:35], v[34:35], v[186:187] op_sel:[0,1] op_sel_hi:[1,1]
	v_pk_mul_f32 v[4:5], v[4:5], v[186:187] op_sel:[0,1] op_sel_hi:[1,1]
	v_pk_mul_f32 v[6:7], v[6:7], v[186:187] op_sel:[0,1] op_sel_hi:[1,1]
	v_pk_mul_f32 v[0:1], v[0:1], v[186:187] op_sel:[0,1] op_sel_hi:[1,1]
	v_pk_mul_f32 v[2:3], v[2:3], v[186:187] op_sel:[0,1] op_sel_hi:[1,1]
	v_pk_mul_f32 v[36:37], v[36:37], v[226:227]
	v_pk_mul_f32 v[38:39], v[38:39], v[228:229]
	v_pk_mul_f32 v[32:33], v[32:33], v[230:231]
	v_pk_mul_f32 v[34:35], v[34:35], v[232:233]
	v_pk_mul_f32 v[4:5], v[4:5], v[234:235]
	v_pk_mul_f32 v[6:7], v[6:7], v[236:237]
	v_pk_mul_f32 v[0:1], v[0:1], v[238:239]
	v_pk_mul_f32 v[2:3], v[2:3], v[240:241]
	global_store_dwordx4 v219, v[36:39], s[14:15] offset:0 nt
	global_store_dwordx4 v219, v[32:35], s[14:15] offset:16 nt
	global_store_dwordx4 v219, v[4:7], s[14:15] offset:512 nt
	global_store_dwordx4 v219, v[0:3], s[14:15] offset:528 nt
	s_nop 1
	s_branch .LBB0_911
